# P1 128x128 tiles: per-K-tile workgroup barrier replaced by a 4-wave LDS counter barrier per virtual block (tiles of a workgroup decoupled inside the K-loop)
# baseline (speedup 1.0000x reference)
; __global__ void __launch_bounds__(512) hymba_fwd(Params p) {
;     __shared__ __attribute__((aligned(16))) unsigned char lds[131072];
;     __shared__ uint4 xb_words;
;     const int G = gridDim.x, bid = blockIdx.x, VG = 2 * G;
;     if (threadIdx.x == 0) xb_words = make_uint4(0u, 0u, 0u, 0u);
;     ...
;     __syncthreads();
_Z9hymba_fwd6Params:
	s_movk_i32 s100, 0x100
	v_cmp_eq_u32_e64 s[94:95], 0, v0
	s_and_saveexec_b64 s[4:5], s[94:95]
	s_cbranch_execz .LBB0_2
	v_mov_b32_e32 v2, 0
	v_mov_b32_e32 v3, v2
	v_mov_b32_e32 v4, v2
	v_mov_b32_e32 v5, v2
	v_mov_b32_e32 v1, 0x20000
	ds_write_b128 v1, v[2:5]
	v_mov_b32_e32 v1, 0x20010
	ds_write_b64 v1, v[2:3]

; #define GLDS_STAGE(st, kt_) do { \
;         _Pragma("unroll") for (int i_ = 0; i_ < FI; ++i_) { \
;             glds16(ap + (size_t)(32 * i_) * lda + (kt_) * 64, l3a + (st) + tid * 16 + i_ * 4096); \
;             glds16(bp + (size_t)(32 * i_) * ldb + (kt_) * 64, l3a + (st) + OPB + tid * 16 + i_ * 4096); } } while (0)
; #define GLDS_STAGE(st, kt_) do { \
;         _Pragma("unroll") for (int i_ = 0; i_ < 4; ++i_) { \
;             glds16(ap + (size_t)(64 * i_) * lda + (kt_) * 64, l3a + (st) + tid * 16 + i_ * 8192); \
;             glds16(bp + (size_t)(64 * i_) * ldb + (kt_) * 64, l3a + (st) + 32768 + tid * 16 + i_ * 8192); } } while (0)
; template <int WT, class Epi>
; DEV void gemm_tile(const bf16_t* __restrict__ A, int lda, const bf16_t* __restrict__ Bt, int ldb, int K, unsigned char* lds, const Epi& epi) {
;     ...
;     constexpr int NSTG = 65536 / STB;
; #pragma unroll
;     for (int s_ = 0; s_ < NSTG - 1; ++s_) if (s_ < nk) GLDS_STAGE(s_ * STB, s_);
;     const int aoff = (wr * WT + fr) * 128, boff = OPB + (wc * WT + fr) * 128, sw = fr & 7;
;     int cur = 0, nxt = (NSTG - 1) * STB;
;     for (int kt = 0; kt < nk; ++kt) {
;         if (NSTG == 4 && kt + 2 < nk) { if (FI == 2) asm volatile("s_waitcnt vmcnt(8)" ::: "memory"); else asm volatile("s_waitcnt vmcnt(0)" ::: "memory"); }
;         else asm volatile("s_waitcnt vmcnt(0)" ::: "memory");
;         __syncthreads();
;         if (kt + NSTG - 1 < nk) GLDS_STAGE(nxt, kt + NSTG - 1);
; #pragma unroll
;         for (int kh = 0; kh < 2; ++kh) {
;             bf16x8 af[FI], bfr[FI];
;             const int ch = ((kh * 4 + fq) ^ sw) << 4;
; #pragma unroll
;             for (int i = 0; i < FI; ++i) { af[i] = *(const bf16x8*)(lds + cur + aoff + i * 2048 + ch); bfr[i] = *(const bf16x8*)(lds + cur + boff + i * 2048 + ch); }
; #pragma unroll
;             for (int mi = 0; mi < FI; ++mi)
; #pragma unroll
;                 for (int ni = 0; ni < FI; ++ni) acc[mi][ni] = __builtin_amdgcn_mfma_f32_16x16x32_bf16(bfr[ni], af[mi], acc[mi][ni], 0, 0, 0);
;         }
;         nxt = cur; cur += STB; if (cur == NSTG * STB) cur = 0;
.LBB0_184:
	s_mov_b32 s46, m0
	s_mov_b32 s42, 0
	s_lshl_b32 s47, s52, 2
	s_add_i32 s47, s47, 0x20010
	v_mov_b32_e32 v145, s47
	v_mov_b32_e32 v146, 1
.Lg128b_0_loop:
	s_add_i32 s40, s53, s42
	s_xor_b32 s43, s42, 0x8000
	v_add_u32_e32 v122, s40, v82
	v_add_u32_e32 v123, s40, v85
	v_add_u32_e32 v143, v122, v81
	v_add_u32_e32 v144, v123, v81
	v_add_u32_e32 v122, v122, v84
	v_add_u32_e32 v123, v123, v84
	s_waitcnt vmcnt(0)
	ds_add_u32 v145, v146
	s_mov_b32 s48, 0
.Lg128b_0_a_spin:
	ds_read_b32 v147, v145
	s_add_u32 s48, s48, 1
	s_waitcnt lgkmcnt(0)
	v_readfirstlane_b32 s47, v147
	s_cmp_ge_u32 s47, s100
	s_cbranch_scc1 .Lg128b_0_a_done
	s_cmp_lt_u32 s48, 0x100000
	s_cbranch_scc1 .Lg128b_0_a_spin
.Lg128b_0_a_done:
	s_addk_i32 s100, 0x100
	v_add_u32_e32 v142, s43, v83
	v_lshl_add_u64 v[124:125], v[78:79], 0, s[4:5]
	v_lshl_add_u64 v[126:127], v[76:77], 0, s[4:5]
	v_readfirstlane_b32 s38, v142
	s_add_i32 s39, s38, 0x4000
	ds_read_b128 v[90:93], v123 offset:16384
	ds_read_b128 v[94:97], v123 offset:18432
	ds_read_b128 v[106:109], v122
	ds_read_b128 v[110:113], v122 offset:2048
	ds_read_b128 v[98:101], v123 offset:20480
	ds_read_b128 v[102:105], v123 offset:22528
	ds_read_b128 v[114:117], v122 offset:4096
	ds_read_b128 v[118:121], v122 offset:6144
	s_waitcnt lgkmcnt(5)
	v_mfma_f32_16x16x32_bf16 v[62:65], v[90:93], v[106:109], v[62:65]
	v_mfma_f32_16x16x32_bf16 v[54:57], v[94:97], v[106:109], v[54:57]
	s_mov_b32 m0, s38
	s_nop 0
	global_load_lds_dwordx4 v[124:125], off
	s_waitcnt lgkmcnt(4)
	v_mfma_f32_16x16x32_bf16 v[38:41], v[90:93], v[110:113], v[38:41]
	v_mfma_f32_16x16x32_bf16 v[34:37], v[94:97], v[110:113], v[34:37]
	s_mov_b32 m0, s39
	s_nop 0
	global_load_lds_dwordx4 v[126:127], off
	s_waitcnt lgkmcnt(2)
	v_mfma_f32_16x16x32_bf16 v[50:53], v[98:101], v[106:109], v[50:53]
	v_mfma_f32_16x16x32_bf16 v[46:49], v[102:105], v[106:109], v[46:49]
	s_add_i32 s40, s38, 0x1000
	s_mov_b32 m0, s40
	v_lshl_add_u64 v[128:129], v[124:125], 0, s[30:31]
	global_load_lds_dwordx4 v[128:129], off
	v_mfma_f32_16x16x32_bf16 v[30:33], v[98:101], v[110:113], v[30:33]
	v_mfma_f32_16x16x32_bf16 v[26:29], v[102:105], v[110:113], v[26:29]
	s_add_i32 s40, s39, 0x1000
	s_mov_b32 m0, s40
	v_lshl_add_u64 v[140:141], v[126:127], 0, s[30:31]
	global_load_lds_dwordx4 v[140:141], off
	s_waitcnt lgkmcnt(1)
	v_mfma_f32_16x16x32_bf16 v[22:25], v[90:93], v[114:117], v[22:25]
	v_mfma_f32_16x16x32_bf16 v[18:21], v[94:97], v[114:117], v[18:21]
	s_add_i32 s40, s38, 0x2000
	s_mov_b32 m0, s40
	v_lshl_add_u64 v[128:129], v[124:125], 0, s[34:35]
	global_load_lds_dwordx4 v[128:129], off
	v_mfma_f32_16x16x32_bf16 v[14:17], v[98:101], v[114:117], v[14:17]
	v_mfma_f32_16x16x32_bf16 v[10:13], v[102:105], v[114:117], v[10:13]
	s_add_i32 s40, s39, 0x2000
	s_mov_b32 m0, s40
	v_lshl_add_u64 v[140:141], v[126:127], 0, s[34:35]
	global_load_lds_dwordx4 v[140:141], off
	s_waitcnt lgkmcnt(0)
	v_mfma_f32_16x16x32_bf16 v[6:9], v[90:93], v[118:121], v[6:9]
	v_mfma_f32_16x16x32_bf16 v[2:5], v[94:97], v[118:121], v[2:5]
	s_add_i32 s40, s38, 0x3000
	s_mov_b32 m0, s40
	v_lshl_add_u64 v[128:129], v[124:125], 0, s[36:37]
	global_load_lds_dwordx4 v[128:129], off
	v_mfma_f32_16x16x32_bf16 v[58:61], v[98:101], v[118:121], v[58:61]
	v_mfma_f32_16x16x32_bf16 v[42:45], v[102:105], v[118:121], v[42:45]
	s_add_i32 s40, s39, 0x3000
	s_mov_b32 m0, s40
	v_lshl_add_u64 v[140:141], v[126:127], 0, s[36:37]
	global_load_lds_dwordx4 v[140:141], off
	v_mov_b32_e32 v122, v143
	v_mov_b32_e32 v123, v144
	ds_read_b128 v[90:93], v123 offset:16384
	ds_read_b128 v[94:97], v123 offset:18432
	ds_read_b128 v[106:109], v122
	ds_read_b128 v[110:113], v122 offset:2048
	ds_read_b128 v[98:101], v123 offset:20480
	ds_read_b128 v[102:105], v123 offset:22528
	ds_read_b128 v[114:117], v122 offset:4096
	ds_read_b128 v[118:121], v122 offset:6144
	s_waitcnt lgkmcnt(5)
	v_mfma_f32_16x16x32_bf16 v[62:65], v[90:93], v[106:109], v[62:65]
	v_mfma_f32_16x16x32_bf16 v[54:57], v[94:97], v[106:109], v[54:57]
	s_waitcnt lgkmcnt(4)
	v_mfma_f32_16x16x32_bf16 v[38:41], v[90:93], v[110:113], v[38:41]
	v_mfma_f32_16x16x32_bf16 v[34:37], v[94:97], v[110:113], v[34:37]
	s_waitcnt lgkmcnt(2)
	v_mfma_f32_16x16x32_bf16 v[50:53], v[98:101], v[106:109], v[50:53]
	v_mfma_f32_16x16x32_bf16 v[46:49], v[102:105], v[106:109], v[46:49]
	v_mfma_f32_16x16x32_bf16 v[30:33], v[98:101], v[110:113], v[30:33]
	v_mfma_f32_16x16x32_bf16 v[26:29], v[102:105], v[110:113], v[26:29]
	s_waitcnt lgkmcnt(1)
	v_mfma_f32_16x16x32_bf16 v[22:25], v[90:93], v[114:117], v[22:25]
	v_mfma_f32_16x16x32_bf16 v[18:21], v[94:97], v[114:117], v[18:21]
	v_mfma_f32_16x16x32_bf16 v[14:17], v[98:101], v[114:117], v[14:17]
	v_mfma_f32_16x16x32_bf16 v[10:13], v[102:105], v[114:117], v[10:13]
	s_waitcnt lgkmcnt(0)
	v_mfma_f32_16x16x32_bf16 v[6:9], v[90:93], v[118:121], v[6:9]
	v_mfma_f32_16x16x32_bf16 v[2:5], v[94:97], v[118:121], v[2:5]
	v_mfma_f32_16x16x32_bf16 v[58:61], v[98:101], v[118:121], v[58:61]
	v_mfma_f32_16x16x32_bf16 v[42:45], v[102:105], v[118:121], v[42:45]
	s_add_u32 s4, s4, 0x80
	s_addc_u32 s5, s5, 0
	s_xor_b32 s42, s42, 0x8000
	s_cmp_lg_u32 s4, 0xf80
	s_cbranch_scc1 .Lg128b_0_loop
	s_mov_b32 m0, s46
	v_add_u32_e32 v102, s53, v85
	v_add_u32_e32 v103, s53, v82
	v_add_u32_e32 v98, v102, v84
	v_add_u32_e32 v104, v103, v84
	s_waitcnt vmcnt(0)
	ds_add_u32 v145, v146
	s_mov_b32 s48, 0

; template <int WT, class Epi>
; DEV void gemm_tile(const bf16_t* __restrict__ A, int lda, const bf16_t* __restrict__ Bt, int ldb, int K, unsigned char* lds, const Epi& epi) {
;     ...
;         for (int kh = 0; kh < 2; ++kh) {
;             bf16x8 af[FI], bfr[FI];
;             const int ch = ((kh * 4 + fq) ^ sw) << 4;
; #pragma unroll
;             for (int i = 0; i < FI; ++i) { af[i] = *(const bf16x8*)(lds + cur + aoff + i * 2048 + ch); bfr[i] = *(const bf16x8*)(lds + cur + boff + i * 2048 + ch); }
; #pragma unroll
;             for (int mi = 0; mi < FI; ++mi)
; #pragma unroll
;                 for (int ni = 0; ni < FI; ++ni) acc[mi][ni] = __builtin_amdgcn_mfma_f32_16x16x32_bf16(bfr[ni], af[mi], acc[mi][ni], 0, 0, 0);
;         }
;         nxt = cur; cur += STB; if (cur == NSTG * STB) cur = 0;
;     }
;     ...
;     __syncthreads();
;     if constexpr (Epi::STAGE) {
;         constexpr int RB = 4 * WT, CPR = RB / 16;
; #pragma unroll
;         for (int mi = 0; mi < FI; ++mi)
; #pragma unroll
;             for (int ni = 0; ni < FI; ++ni) {
;                 const int row = wr * WT + mi * 16 + fr, col = wc * WT + ni * 16 + fq * 4;
;                 const f32x4 v = epi.xform(row, col, acc[mi][ni]);
;                 uint2 w; w.x = cvt_pk_bf16(v[0], v[1]); w.y = cvt_pk_bf16(v[2], v[3]);
;                 *(uint2*)(lds + row * RB + ((((col >> 3) ^ (row & (CPR - 1))) << 4) | (((col >> 2) & 1) << 3))) = w;
;             }
;         __syncthreads();
; #pragma unroll
;         for (int i = 0; i < (2 * WT * CPR) / 256; ++i) {
;             const int idx = tid + 256 * i, row = idx / CPR, cp = idx % CPR, c = cp ^ (row & (CPR - 1));
;             const uint4 d = *(const uint4*)(lds + row * RB + (cp << 4));
;             *(uint4*)(epi.obase + (size_t)row * epi.old + c * 8) = epi.finish(row, c * 8, d);
;         }
;         __syncthreads();
;     } else {
; #pragma unroll
;         for (int mi = 0; mi < FI; ++mi)
; #pragma unroll
;             for (int ni = 0; ni < FI; ++ni) epi(wr * WT + mi * 16 + fr, wc * WT + ni * 16 + fq * 4, acc[mi][ni]);
;     DEV void operator()(int r, int c, f32x4 v) const {
;         const int row = m0 + r, col = n0 + c;
;         if (col < D) {
;             __builtin_nontemporal_store(v, (f32x4*)(out + O_MK + (size_t)row * D + col));
;             store_bf4(mkb + (size_t)row * LDB + col, v);
;         } else {
.Lg128b_0_t_done:
	s_addk_i32 s100, 0x100
	ds_read_b128 v[76:79], v98 offset:49152
	ds_read_b128 v[90:93], v98 offset:51200
	ds_read_b128 v[82:85], v104 offset:32768
	ds_read_b128 v[94:97], v98 offset:53248
	ds_read_b128 v[98:101], v98 offset:55296
	s_waitcnt lgkmcnt(2)
	v_mfma_f32_16x16x32_bf16 v[62:65], v[76:79], v[82:85], v[62:65]
	v_add_u32_e32 v102, v102, v81
	v_add_u32_e32 v81, v103, v81
	s_lshl_b32 s11, s8, 7
	v_mfma_f32_16x16x32_bf16 v[54:57], v[90:93], v[82:85], v[54:57]
	s_lshl_b32 s4, s7, 7
	s_cmpk_gt_u32 s6, 0x7f
	s_cselect_b64 s[6:7], -1, 0
	s_waitcnt lgkmcnt(1)
	v_mfma_f32_16x16x32_bf16 v[50:53], v[94:97], v[82:85], v[50:53]
	ds_read_b128 v[106:109], v81 offset:34816
	s_and_b64 vcc, exec, s[6:7]
	ds_read_b128 v[110:113], v81 offset:38912
	s_waitcnt lgkmcnt(2)
	v_mfma_f32_16x16x32_bf16 v[46:49], v[98:101], v[82:85], v[46:49]
	ds_read_b128 v[82:85], v104 offset:34816
	s_waitcnt lgkmcnt(0)
	v_mfma_f32_16x16x32_bf16 v[38:41], v[76:79], v[82:85], v[38:41]
	v_mfma_f32_16x16x32_bf16 v[34:37], v[90:93], v[82:85], v[34:37]
	v_mfma_f32_16x16x32_bf16 v[30:33], v[94:97], v[82:85], v[30:33]
	v_mfma_f32_16x16x32_bf16 v[26:29], v[98:101], v[82:85], v[26:29]
	ds_read_b128 v[82:85], v104 offset:36864
	s_waitcnt lgkmcnt(0)
	v_mfma_f32_16x16x32_bf16 v[22:25], v[76:79], v[82:85], v[22:25]
	v_mfma_f32_16x16x32_bf16 v[18:21], v[90:93], v[82:85], v[18:21]
	v_mfma_f32_16x16x32_bf16 v[14:17], v[94:97], v[82:85], v[14:17]
	v_mfma_f32_16x16x32_bf16 v[10:13], v[98:101], v[82:85], v[10:13]
	ds_read_b128 v[82:85], v104 offset:38912
	s_waitcnt lgkmcnt(0)
	v_mfma_f32_16x16x32_bf16 v[6:9], v[76:79], v[82:85], v[6:9]
	ds_read_b128 v[76:79], v102 offset:49152
	v_mfma_f32_16x16x32_bf16 v[2:5], v[90:93], v[82:85], v[2:5]
	v_mfma_f32_16x16x32_bf16 v[90:93], v[94:97], v[82:85], v[58:61]
	v_mfma_f32_16x16x32_bf16 v[94:97], v[98:101], v[82:85], v[42:45]
	ds_read_b128 v[82:85], v102 offset:51200
	ds_read_b128 v[98:101], v102 offset:53248
	ds_read_b128 v[102:105], v102 offset:55296
	ds_read_b128 v[42:45], v81 offset:32768
	s_waitcnt lgkmcnt(0)
	v_mfma_f32_16x16x32_bf16 v[62:65], v[76:79], v[42:45], v[62:65]
	v_mfma_f32_16x16x32_bf16 v[58:61], v[82:85], v[42:45], v[54:57]
	v_mfma_f32_16x16x32_bf16 v[54:57], v[98:101], v[42:45], v[50:53]
	v_mfma_f32_16x16x32_bf16 v[50:53], v[102:105], v[42:45], v[46:49]
	v_mfma_f32_16x16x32_bf16 v[46:49], v[76:79], v[106:109], v[38:41]
	v_mfma_f32_16x16x32_bf16 v[42:45], v[82:85], v[106:109], v[34:37]
	v_mfma_f32_16x16x32_bf16 v[38:41], v[98:101], v[106:109], v[30:33]
	v_mfma_f32_16x16x32_bf16 v[34:37], v[102:105], v[106:109], v[26:29]
	ds_read_b128 v[106:109], v81 offset:36864
	v_and_b32_e32 v81, 64, v80
	v_add_u32_e32 v80, s11, v89
	s_waitcnt lgkmcnt(0)
	v_mfma_f32_16x16x32_bf16 v[30:33], v[76:79], v[106:109], v[22:25]
	s_barrier
	v_mfma_f32_16x16x32_bf16 v[26:29], v[82:85], v[106:109], v[18:21]
	v_mfma_f32_16x16x32_bf16 v[22:25], v[98:101], v[106:109], v[14:17]
	s_nop 2
	v_lshlrev_b32_e32 v14, 2, v74
	v_mfma_f32_16x16x32_bf16 v[18:21], v[102:105], v[106:109], v[10:13]
	v_or3_b32 v74, v14, v81, s4
	s_mov_b64 s[4:5], -1
	v_ashrrev_i32_e32 v81, 31, v80
	v_mfma_f32_16x16x32_bf16 v[10:13], v[82:85], v[110:113], v[2:5]
	v_ashrrev_i32_e32 v84, 8, v80
	v_ashrrev_i32_e32 v85, 31, v84
	s_nop 0
	v_and_b32_e32 v2, 0xcf, v80
	v_mfma_f32_16x16x32_bf16 v[14:17], v[76:79], v[110:113], v[6:9]
	v_lshlrev_b32_e32 v82, 1, v2
	v_add_u32_e32 v78, 0xfffff800, v74
	v_mfma_f32_16x16x32_bf16 v[6:9], v[98:101], v[110:113], v[90:93]
	v_mfma_f32_16x16x32_bf16 v[2:5], v[102:105], v[110:113], v[94:97]
	s_cbranch_vccz .LBB0_187
	v_lshlrev_b64 v[76:77], 13, v[80:81]
	v_lshl_add_u64 v[76:77], s[18:19], 0, v[76:77]
	v_mov_b32_e32 v79, v75
	v_lshl_add_u64 v[76:77], v[78:79], 2, v[76:77]
	global_store_dwordx4 v[76:77], v[62:65], off nt
	v_lshlrev_b64 v[76:77], 11, v[84:85]
	v_lshl_add_u64 v[76:77], v[76:77], 0, v[78:79]
	v_mad_u64_u32 v[90:91], s[4:5], v76, s60, v[162:163]
	v_mad_i32_i24 v91, v77, s60, v91
	v_mov_b32_e32 v83, v75
	v_lshl_add_u64 v[76:77], v[90:91], 0, v[82:83]
	v_cvt_pk_bf16_f32 v79, v62, s0
	global_store_short v[76:77], v79, off
	v_cvt_pk_bf16_f32 v79, v63, s0
	global_store_short v[76:77], v79, off offset:576
	v_cvt_pk_bf16_f32 v79, v64, s0
	global_store_short v[76:77], v79, off offset:1152
	v_cvt_pk_bf16_f32 v79, v65, s0
	global_store_short v[76:77], v79, off offset:1728
	s_mov_b64 s[4:5], 0

; template <int WT, class Epi>
; DEV void gemm_tile(const bf16_t* __restrict__ A, int lda, const bf16_t* __restrict__ Bt, int ldb, int K, unsigned char* lds, const Epi& epi) {
;     ...
;     for (int kt = 0; kt < nk; ++kt) {
;         if (NSTG == 4 && kt + 2 < nk) { if (FI == 2) asm volatile("s_waitcnt vmcnt(8)" ::: "memory"); else asm volatile("s_waitcnt vmcnt(0)" ::: "memory"); }
;         else asm volatile("s_waitcnt vmcnt(0)" ::: "memory");
;         __syncthreads();
.Lg128b_1_loop:
	s_add_i32 s40, s53, s42
	s_xor_b32 s43, s42, 0x8000
	v_add_u32_e32 v122, s40, v84
	v_add_u32_e32 v123, s40, v89
	v_add_u32_e32 v143, v122, v82
	v_add_u32_e32 v144, v123, v82
	v_add_u32_e32 v122, v122, v85
	v_add_u32_e32 v123, v123, v85
	s_waitcnt vmcnt(0)
	ds_add_u32 v145, v146
	s_mov_b32 s48, 0

; #define GLDS_STAGE(st, kt_) do { \
;         _Pragma("unroll") for (int i_ = 0; i_ < FI; ++i_) { \
;             glds16(ap + (size_t)(32 * i_) * lda + (kt_) * 64, l3a + (st) + tid * 16 + i_ * 4096); \
;             glds16(bp + (size_t)(32 * i_) * ldb + (kt_) * 64, l3a + (st) + OPB + tid * 16 + i_ * 4096); } } while (0)
; #define GLDS_STAGE(st, kt_) do { \
;         _Pragma("unroll") for (int i_ = 0; i_ < 4; ++i_) { \
;             glds16(ap + (size_t)(64 * i_) * lda + (kt_) * 64, l3a + (st) + tid * 16 + i_ * 8192); \
;             glds16(bp + (size_t)(64 * i_) * ldb + (kt_) * 64, l3a + (st) + 32768 + tid * 16 + i_ * 8192); } } while (0)
; template <int WT, class Epi>
; DEV void gemm_tile(const bf16_t* __restrict__ A, int lda, const bf16_t* __restrict__ Bt, int ldb, int K, unsigned char* lds, const Epi& epi) {
;     ...
;     for (int kt = 0; kt < nk; ++kt) {
;         if (NSTG == 4 && kt + 2 < nk) { if (FI == 2) asm volatile("s_waitcnt vmcnt(8)" ::: "memory"); else asm volatile("s_waitcnt vmcnt(0)" ::: "memory"); }
;         else asm volatile("s_waitcnt vmcnt(0)" ::: "memory");
;         __syncthreads();
;         if (kt + NSTG - 1 < nk) GLDS_STAGE(nxt, kt + NSTG - 1);
; #pragma unroll
;         for (int kh = 0; kh < 2; ++kh) {
;             bf16x8 af[FI], bfr[FI];
;             const int ch = ((kh * 4 + fq) ^ sw) << 4;
; #pragma unroll
;             for (int i = 0; i < FI; ++i) { af[i] = *(const bf16x8*)(lds + cur + aoff + i * 2048 + ch); bfr[i] = *(const bf16x8*)(lds + cur + boff + i * 2048 + ch); }
; #pragma unroll
;             for (int mi = 0; mi < FI; ++mi)
; #pragma unroll
;                 for (int ni = 0; ni < FI; ++ni) acc[mi][ni] = __builtin_amdgcn_mfma_f32_16x16x32_bf16(bfr[ni], af[mi], acc[mi][ni], 0, 0, 0);
;         }
;         nxt = cur; cur += STB; if (cur == NSTG * STB) cur = 0;
.Lg128b_1_a_done:
	s_addk_i32 s100, 0x100
	v_add_u32_e32 v142, s43, v83
	v_lshl_add_u64 v[124:125], v[78:79], 0, s[4:5]
	v_lshl_add_u64 v[126:127], v[76:77], 0, s[4:5]
	v_readfirstlane_b32 s38, v142
	s_add_i32 s39, s38, 0x4000
	ds_read_b128 v[90:93], v123 offset:16384
	ds_read_b128 v[94:97], v123 offset:18432
	ds_read_b128 v[106:109], v122
	ds_read_b128 v[110:113], v122 offset:2048
	ds_read_b128 v[98:101], v123 offset:20480
	ds_read_b128 v[102:105], v123 offset:22528
	ds_read_b128 v[114:117], v122 offset:4096
	ds_read_b128 v[118:121], v122 offset:6144
	s_waitcnt lgkmcnt(5)
	v_mfma_f32_16x16x32_bf16 v[62:65], v[90:93], v[106:109], v[62:65]
	v_mfma_f32_16x16x32_bf16 v[54:57], v[94:97], v[106:109], v[54:57]
	s_mov_b32 m0, s38
	s_nop 0
	global_load_lds_dwordx4 v[124:125], off
	s_waitcnt lgkmcnt(4)
	v_mfma_f32_16x16x32_bf16 v[38:41], v[90:93], v[110:113], v[38:41]
	v_mfma_f32_16x16x32_bf16 v[34:37], v[94:97], v[110:113], v[34:37]
	s_mov_b32 m0, s39
	s_nop 0
	global_load_lds_dwordx4 v[126:127], off
	s_waitcnt lgkmcnt(2)
	v_mfma_f32_16x16x32_bf16 v[50:53], v[98:101], v[106:109], v[50:53]
	v_mfma_f32_16x16x32_bf16 v[46:49], v[102:105], v[106:109], v[46:49]
	s_add_i32 s40, s38, 0x1000
	s_mov_b32 m0, s40
	v_lshl_add_u64 v[128:129], v[124:125], 0, s[30:31]
	global_load_lds_dwordx4 v[128:129], off
	v_mfma_f32_16x16x32_bf16 v[30:33], v[98:101], v[110:113], v[30:33]
	v_mfma_f32_16x16x32_bf16 v[26:29], v[102:105], v[110:113], v[26:29]
	s_add_i32 s40, s39, 0x1000
	s_mov_b32 m0, s40
	v_lshl_add_u64 v[140:141], v[126:127], 0, s[30:31]
	global_load_lds_dwordx4 v[140:141], off
	s_waitcnt lgkmcnt(1)
	v_mfma_f32_16x16x32_bf16 v[22:25], v[90:93], v[114:117], v[22:25]
	v_mfma_f32_16x16x32_bf16 v[18:21], v[94:97], v[114:117], v[18:21]
	s_add_i32 s40, s38, 0x2000
	s_mov_b32 m0, s40
	v_lshl_add_u64 v[128:129], v[124:125], 0, s[34:35]
	global_load_lds_dwordx4 v[128:129], off
	v_mfma_f32_16x16x32_bf16 v[14:17], v[98:101], v[114:117], v[14:17]
	v_mfma_f32_16x16x32_bf16 v[10:13], v[102:105], v[114:117], v[10:13]
	s_add_i32 s40, s39, 0x2000
	s_mov_b32 m0, s40
	v_lshl_add_u64 v[140:141], v[126:127], 0, s[34:35]
	global_load_lds_dwordx4 v[140:141], off
	s_waitcnt lgkmcnt(0)
	v_mfma_f32_16x16x32_bf16 v[6:9], v[90:93], v[118:121], v[6:9]
	v_mfma_f32_16x16x32_bf16 v[2:5], v[94:97], v[118:121], v[2:5]
	s_add_i32 s40, s38, 0x3000
	s_mov_b32 m0, s40
	v_lshl_add_u64 v[128:129], v[124:125], 0, s[36:37]
	global_load_lds_dwordx4 v[128:129], off
	v_mfma_f32_16x16x32_bf16 v[58:61], v[98:101], v[118:121], v[58:61]
	v_mfma_f32_16x16x32_bf16 v[42:45], v[102:105], v[118:121], v[42:45]
	s_add_i32 s40, s39, 0x3000
	s_mov_b32 m0, s40
	v_lshl_add_u64 v[140:141], v[126:127], 0, s[36:37]
	global_load_lds_dwordx4 v[140:141], off
	v_mov_b32_e32 v122, v143
	v_mov_b32_e32 v123, v144
	ds_read_b128 v[90:93], v123 offset:16384
	ds_read_b128 v[94:97], v123 offset:18432
	ds_read_b128 v[106:109], v122
	ds_read_b128 v[110:113], v122 offset:2048
	ds_read_b128 v[98:101], v123 offset:20480
	ds_read_b128 v[102:105], v123 offset:22528
	ds_read_b128 v[114:117], v122 offset:4096
	ds_read_b128 v[118:121], v122 offset:6144
	s_waitcnt lgkmcnt(5)
	v_mfma_f32_16x16x32_bf16 v[62:65], v[90:93], v[106:109], v[62:65]
	v_mfma_f32_16x16x32_bf16 v[54:57], v[94:97], v[106:109], v[54:57]
	s_waitcnt lgkmcnt(4)
	v_mfma_f32_16x16x32_bf16 v[38:41], v[90:93], v[110:113], v[38:41]
	v_mfma_f32_16x16x32_bf16 v[34:37], v[94:97], v[110:113], v[34:37]
	s_waitcnt lgkmcnt(2)
	v_mfma_f32_16x16x32_bf16 v[50:53], v[98:101], v[106:109], v[50:53]
	v_mfma_f32_16x16x32_bf16 v[46:49], v[102:105], v[106:109], v[46:49]
	v_mfma_f32_16x16x32_bf16 v[30:33], v[98:101], v[110:113], v[30:33]
	v_mfma_f32_16x16x32_bf16 v[26:29], v[102:105], v[110:113], v[26:29]
	s_waitcnt lgkmcnt(1)
	v_mfma_f32_16x16x32_bf16 v[22:25], v[90:93], v[114:117], v[22:25]
	v_mfma_f32_16x16x32_bf16 v[18:21], v[94:97], v[114:117], v[18:21]
	v_mfma_f32_16x16x32_bf16 v[14:17], v[98:101], v[114:117], v[14:17]
	v_mfma_f32_16x16x32_bf16 v[10:13], v[102:105], v[114:117], v[10:13]
	s_waitcnt lgkmcnt(0)
	v_mfma_f32_16x16x32_bf16 v[6:9], v[90:93], v[118:121], v[6:9]
	v_mfma_f32_16x16x32_bf16 v[2:5], v[94:97], v[118:121], v[2:5]
	v_mfma_f32_16x16x32_bf16 v[58:61], v[98:101], v[118:121], v[58:61]
	v_mfma_f32_16x16x32_bf16 v[42:45], v[102:105], v[118:121], v[42:45]
	s_add_u32 s4, s4, 0x80
	s_addc_u32 s5, s5, 0
	s_xor_b32 s42, s42, 0x8000
	s_cmp_lg_u32 s4, 0xf80
	s_cbranch_scc1 .Lg128b_1_loop
	s_mov_b32 m0, s46
	v_add_u32_e32 v83, s53, v89
	v_add_u32_e32 v89, v83, v85
	s_waitcnt vmcnt(0)
	ds_add_u32 v145, v146
	s_mov_b32 s48, 0

; template <int WT, class Epi>
; DEV void gemm_tile(const bf16_t* __restrict__ A, int lda, const bf16_t* __restrict__ Bt, int ldb, int K, unsigned char* lds, const Epi& epi) {
;     ...
;         for (int kh = 0; kh < 2; ++kh) {
;             bf16x8 af[FI], bfr[FI];
;             const int ch = ((kh * 4 + fq) ^ sw) << 4;
; #pragma unroll
;             for (int i = 0; i < FI; ++i) { af[i] = *(const bf16x8*)(lds + cur + aoff + i * 2048 + ch); bfr[i] = *(const bf16x8*)(lds + cur + boff + i * 2048 + ch); }
; #pragma unroll
;             for (int mi = 0; mi < FI; ++mi)
; #pragma unroll
;                 for (int ni = 0; ni < FI; ++ni) acc[mi][ni] = __builtin_amdgcn_mfma_f32_16x16x32_bf16(bfr[ni], af[mi], acc[mi][ni], 0, 0, 0);
;         }
;         nxt = cur; cur += STB; if (cur == NSTG * STB) cur = 0;
;     }
;     ...
;     __syncthreads();
;     if constexpr (Epi::STAGE) {
;         constexpr int RB = 4 * WT, CPR = RB / 16;
; #pragma unroll
;         for (int mi = 0; mi < FI; ++mi)
; #pragma unroll
;             for (int ni = 0; ni < FI; ++ni) {
;                 const int row = wr * WT + mi * 16 + fr, col = wc * WT + ni * 16 + fq * 4;
;                 const f32x4 v = epi.xform(row, col, acc[mi][ni]);
;                 uint2 w; w.x = cvt_pk_bf16(v[0], v[1]); w.y = cvt_pk_bf16(v[2], v[3]);
;                 *(uint2*)(lds + row * RB + ((((col >> 3) ^ (row & (CPR - 1))) << 4) | (((col >> 2) & 1) << 3))) = w;
;             }
;         __syncthreads();
; #pragma unroll
;         for (int i = 0; i < (2 * WT * CPR) / 256; ++i) {
;             const int idx = tid + 256 * i, row = idx / CPR, cp = idx % CPR, c = cp ^ (row & (CPR - 1));
;             const uint4 d = *(const uint4*)(lds + row * RB + (cp << 4));
;             *(uint4*)(epi.obase + (size_t)row * epi.old + c * 8) = epi.finish(row, c * 8, d);
;         }
;         __syncthreads();
;     } else {
; #pragma unroll
;         for (int mi = 0; mi < FI; ++mi)
; #pragma unroll
;             for (int ni = 0; ni < FI; ++ni) epi(wr * WT + mi * 16 + fr, wc * WT + ni * 16 + fq * 4, acc[mi][ni]);
;     DEV void operator()(int r, int c, f32x4 v) const {
;         const int row = m0 + r, col = n0 + c;
;         if (col < NPJ) {
;             store_bf4(proj + (size_t)row * NPJ + col, v);
;             const bool isconv = col < 3072, ispool = (col >= C_U && col < C_ZB);
;             if (isconv || ispool) {
;                 if (row < TP) {
.Lg128b_1_t_done:
	s_addk_i32 s100, 0x100
	ds_read_b128 v[76:79], v89 offset:49152
	ds_read_b128 v[94:97], v89 offset:51200
	ds_read_b128 v[98:101], v89 offset:53248
	ds_read_b128 v[102:105], v89 offset:55296
	v_add_u32_e32 v84, s53, v84
	v_add_u32_e32 v85, v84, v85
	ds_read_b128 v[90:93], v85 offset:32768
	v_add_u32_e32 v89, v84, v82
	ds_read_b128 v[110:113], v89 offset:36864
	s_waitcnt lgkmcnt(1)
	v_mfma_f32_16x16x32_bf16 v[62:65], v[76:79], v[90:93], v[62:65]
	ds_read_b128 v[114:117], v89 offset:38912
	s_lshl_b32 s4, s6, 7
	s_and_b32 s26, s10, 0x7ffffe0
	v_mfma_f32_16x16x32_bf16 v[54:57], v[94:97], v[90:93], v[54:57]
	s_cmpk_lg_i32 s26, 0x80
	s_cselect_b64 s[44:45], -1, 0
	v_mfma_f32_16x16x32_bf16 v[50:53], v[98:101], v[90:93], v[50:53]
	v_mfma_f32_16x16x32_bf16 v[46:49], v[102:105], v[90:93], v[46:49]
	ds_read_b128 v[90:93], v85 offset:34816
	s_waitcnt lgkmcnt(0)
	v_mfma_f32_16x16x32_bf16 v[38:41], v[76:79], v[90:93], v[38:41]
	v_mfma_f32_16x16x32_bf16 v[34:37], v[94:97], v[90:93], v[34:37]
	v_mfma_f32_16x16x32_bf16 v[30:33], v[98:101], v[90:93], v[30:33]
	v_mfma_f32_16x16x32_bf16 v[26:29], v[102:105], v[90:93], v[26:29]
	ds_read_b128 v[90:93], v85 offset:36864
	s_waitcnt lgkmcnt(0)
	v_mfma_f32_16x16x32_bf16 v[22:25], v[76:79], v[90:93], v[22:25]
	v_mfma_f32_16x16x32_bf16 v[18:21], v[94:97], v[90:93], v[18:21]
	v_mfma_f32_16x16x32_bf16 v[14:17], v[98:101], v[90:93], v[14:17]
	v_mfma_f32_16x16x32_bf16 v[10:13], v[102:105], v[90:93], v[10:13]
	ds_read_b128 v[90:93], v85 offset:38912
	s_waitcnt lgkmcnt(0)
	v_mfma_f32_16x16x32_bf16 v[6:9], v[76:79], v[90:93], v[6:9]
	v_add_u32_e32 v76, v83, v82
	ds_read_b128 v[82:85], v76 offset:51200
	ds_read_b128 v[106:109], v76 offset:55296
	v_mfma_f32_16x16x32_bf16 v[2:5], v[94:97], v[90:93], v[2:5]
	v_mfma_f32_16x16x32_bf16 v[94:97], v[98:101], v[90:93], v[58:61]
	ds_read_b128 v[98:101], v76 offset:49152
	v_mfma_f32_16x16x32_bf16 v[90:93], v[102:105], v[90:93], v[42:45]
	ds_read_b128 v[102:105], v76 offset:53248
	ds_read_b128 v[76:79], v89 offset:34816
	s_nop 0
	ds_read_b128 v[42:45], v89 offset:32768
	s_waitcnt lgkmcnt(0)
	v_mfma_f32_16x16x32_bf16 v[62:65], v[98:101], v[42:45], v[62:65]
	s_barrier
	v_mfma_f32_16x16x32_bf16 v[58:61], v[82:85], v[42:45], v[54:57]
	v_mfma_f32_16x16x32_bf16 v[54:57], v[102:105], v[42:45], v[50:53]
	v_mfma_f32_16x16x32_bf16 v[50:53], v[106:109], v[42:45], v[46:49]
	v_mfma_f32_16x16x32_bf16 v[46:49], v[98:101], v[76:79], v[38:41]
	v_mfma_f32_16x16x32_bf16 v[42:45], v[82:85], v[76:79], v[34:37]
	v_mfma_f32_16x16x32_bf16 v[38:41], v[102:105], v[76:79], v[30:33]
	v_mfma_f32_16x16x32_bf16 v[34:37], v[106:109], v[76:79], v[26:29]
	v_and_b32_e32 v76, 64, v80
	v_mfma_f32_16x16x32_bf16 v[26:29], v[82:85], v[110:113], v[18:21]
	s_nop 2
	v_lshlrev_b32_e32 v18, 2, v74
	v_add_u32_e32 v74, s68, v81
	v_or3_b32 v76, v18, v76, s4
	v_mfma_f32_16x16x32_bf16 v[30:33], v[98:101], v[110:113], v[22:25]
	v_ashrrev_i32_e32 v77, 31, v76
	v_cmp_lt_i32_e32 vcc, s62, v76
	s_and_b64 s[38:39], s[44:45], vcc
	v_mfma_f32_16x16x32_bf16 v[22:25], v[102:105], v[110:113], v[14:17]
	v_cmp_gt_i32_e64 s[12:13], s57, v74
	s_nor_b64 s[8:9], s[12:13], s[38:39]
	s_nop 0
	v_mad_i64_i32 v[14:15], s[4:5], v74, s58, v[172:173]
	v_lshl_add_u64 v[78:79], v[76:77], 1, v[14:15]
	v_mfma_f32_16x16x32_bf16 v[18:21], v[106:109], v[110:113], v[10:13]
	v_cmp_gt_i32_e64 s[4:5], s61, v76
	s_nop 1
	v_cvt_pk_bf16_f32 v10, v62, v63
	v_cvt_pk_bf16_f32 v11, v64, v65
	global_store_dwordx2 v[78:79], v[10:11], off
	v_mfma_f32_16x16x32_bf16 v[10:13], v[82:85], v[114:117], v[2:5]
	s_nop 2
	v_add_u32_e32 v2, 0xffffe000, v74
	v_mfma_f32_16x16x32_bf16 v[14:17], v[98:101], v[114:117], v[6:9]
	v_lshrrev_b32_e32 v82, 2, v2
	v_mfma_f32_16x16x32_bf16 v[6:9], v[102:105], v[114:117], v[94:97]
	v_mfma_f32_16x16x32_bf16 v[2:5], v[106:109], v[114:117], v[90:93]
	s_and_saveexec_b64 s[6:7], s[8:9]
	s_cbranch_execz .LBB0_234
	v_and_b32_e32 v74, 3, v80
	s_and_saveexec_b64 s[8:9], s[4:5]
	s_xor_b64 s[8:9], exec, s[8:9]
	s_cbranch_execz .LBB0_232
	v_cmp_ne_u32_e32 vcc, 0, v74
	s_and_saveexec_b64 s[10:11], vcc
	s_cbranch_execz .LBB0_231
	v_lshl_add_u32 v83, v82, 1, v82
	v_add3_u32 v74, v74, v83, -1
	v_mov_b64_e32 v[84:85], s[22:23]
	v_mad_u64_u32 v[84:85], s[40:41], v74, s58, v[84:85]
	v_lshl_add_u64 v[84:85], v[76:77], 2, v[84:85]
	global_store_dwordx4 v[84:85], v[62:65], off

; __global__ void __launch_bounds__(512) hymba_fwd(Params p) {
;     __shared__ __attribute__((aligned(16))) unsigned char lds[131072];
;     __shared__ uint4 xb_words;
	.amdhsa_kernel _Z9hymba_fwd6Params
		.amdhsa_group_segment_fixed_size 131104
		.amdhsa_private_segment_fixed_size 0
		.amdhsa_kernarg_size 472
		.amdhsa_user_sgpr_count 2
		.amdhsa_user_sgpr_dispatch_ptr 0
		.amdhsa_user_sgpr_queue_ptr 0
		.amdhsa_user_sgpr_kernarg_segment_ptr 1
		.amdhsa_user_sgpr_dispatch_id 0
		.amdhsa_user_sgpr_kernarg_preload_length 0
		.amdhsa_user_sgpr_kernarg_preload_offset 0
		.amdhsa_user_sgpr_private_segment_size 0
		.amdhsa_uses_dynamic_stack 0
		.amdhsa_enable_private_segment 0
		.amdhsa_system_sgpr_workgroup_id_x 1
		.amdhsa_system_sgpr_workgroup_id_y 0
		.amdhsa_system_sgpr_workgroup_id_z 0
		.amdhsa_system_sgpr_workgroup_info 0
		.amdhsa_system_vgpr_workitem_id 0
		.amdhsa_next_free_vgpr 253
		.amdhsa_next_free_sgpr 102
		.amdhsa_accum_offset 256
		.amdhsa_reserve_vcc 1
		.amdhsa_float_round_mode_32 0
		.amdhsa_float_round_mode_16_64 0
		.amdhsa_float_denorm_mode_32 3
		.amdhsa_float_denorm_mode_16_64 3
		.amdhsa_dx10_clamp 1
		.amdhsa_ieee_mode 1
		.amdhsa_fp16_overflow 0
		.amdhsa_tg_split 0
		.amdhsa_exception_fp_ieee_invalid_op 0
		.amdhsa_exception_fp_denorm_src 0
		.amdhsa_exception_fp_ieee_div_zero 0
		.amdhsa_exception_fp_ieee_overflow 0
		.amdhsa_exception_fp_ieee_underflow 0
		.amdhsa_exception_fp_ieee_inexact 0
		.amdhsa_exception_int_div_zero 0
	.end_amdhsa_kernel

; __global__ void __launch_bounds__(512) hymba_fwd(Params p) {
;     __shared__ __attribute__((aligned(16))) unsigned char lds[131072];
;     __shared__ uint4 xb_words;
amdhsa.kernels:
  - .agpr_count:     0
    .args:
      - .offset:         0
        .size:           216
        .value_kind:     by_value
      - .offset:         216
        .size:           4
        .value_kind:     hidden_block_count_x
      - .offset:         220
        .size:           4
        .value_kind:     hidden_block_count_y
      - .offset:         224
        .size:           4
        .value_kind:     hidden_block_count_z
      - .offset:         228
        .size:           2
        .value_kind:     hidden_group_size_x
      - .offset:         230
        .size:           2
        .value_kind:     hidden_group_size_y
      - .offset:         232
        .size:           2
        .value_kind:     hidden_group_size_z
      - .offset:         234
        .size:           2
        .value_kind:     hidden_remainder_x
      - .offset:         236
        .size:           2
        .value_kind:     hidden_remainder_y
      - .offset:         238
        .size:           2
        .value_kind:     hidden_remainder_z
      - .offset:         256
        .size:           8
        .value_kind:     hidden_global_offset_x
      - .offset:         264
        .size:           8
        .value_kind:     hidden_global_offset_y
      - .offset:         272
        .size:           8
        .value_kind:     hidden_global_offset_z
      - .offset:         280
        .size:           2
        .value_kind:     hidden_grid_dims
    .group_segment_fixed_size: 131104
    .kernarg_segment_align: 8
    .kernarg_segment_size: 472
    .language:       OpenCL C
    .language_version:
      - 2
      - 0
    .max_flat_workgroup_size: 512
    .name:           _Z9hymba_fwd6Params
    .private_segment_fixed_size: 0
    .sgpr_count:     108
    .sgpr_spill_count: 4
    .symbol:         _Z9hymba_fwd6Params.kd
    .uniform_work_group_size: 1
    .uses_dynamic_stack: false
    .vgpr_count:     253
    .vgpr_spill_count: 0
    .wavefront_size: 64
